# retention state scan software-pipelined: four 8-load batches in flight, SGPR-base addressing (on top of early buffer_inv)
# speedup vs baseline: 1.0034x; 1.0034x over previous
; __device__ __forceinline__ unsigned xb_add(unsigned* p, unsigned v) { return __hip_atomic_fetch_add(p, v, __ATOMIC_RELAXED, __HIP_MEMORY_SCOPE_AGENT); }
; __device__ __forceinline__ void xcd_barrier(const XcdBarrier& b) {
;     asm volatile("s_waitcnt vmcnt(0)" ::: "memory");
;     __syncthreads();
;     const unsigned long long bp_ = (unsigned long long)b.bar; unsigned blo_ = __builtin_amdgcn_readfirstlane((unsigned)bp_), bhi_ = __builtin_amdgcn_readfirstlane((unsigned)(bp_ >> 32));
;     asm volatile("" : "+s"(blo_), "+s"(bhi_)); unsigned* bar = (unsigned*)(((unsigned long long)bhi_ << 32) | blo_);
;     if (threadIdx.x == 0) {
;         __builtin_amdgcn_s_waitcnt(0);
;         unsigned nloc = b.st[0], nx = b.st[1];
;         if (nloc == 0u) { xcd_barrier_complete(bar, b.x, nloc, nx); b.st[0] = nloc; b.st[1] = nx; }
;         const unsigned old = xb_add(&bar[XB_XSUB(b.x)], 1u);
;         const unsigned gen = old / nloc;
;         if (old + 1u == (gen + 1u) * nloc) {
.LBB0_1029:
	s_waitcnt vmcnt(10)
	v_mov_b32_e32 v0, 0x22600
	ds_read2_b32 v[0:1], v0 offset0:70 offset1:71
	v_mov_b32_e32 v2, 0x22568
	ds_read_b32 v2, v2
	s_waitcnt vmcnt(0)
	s_waitcnt lgkmcnt(0)
	v_readfirstlane_b32 s0, v0
	v_readfirstlane_b32 s1, v1
	s_add_u32 s34, s0, 0x4000
	v_readfirstlane_b32 s33, v2
	s_addc_u32 s35, s1, 0
	s_barrier
	s_mov_b64 s[4:5], exec
	v_readlane_b32 s0, v254, 3
	v_readlane_b32 s1, v254, 4
	s_and_b64 s[0:1], s[4:5], s[0:1]
	s_mov_b64 exec, s[0:1]
	s_cbranch_execz .LBB0_1059
	v_mov_b32_e32 v0, 0x22560
	s_waitcnt vmcnt(0) expcnt(0) lgkmcnt(0)
	buffer_inv sc1
	ds_read_b32 v2, v0
	v_mov_b32_e32 v0, 0x22564
	ds_read_b32 v0, v0
	s_waitcnt lgkmcnt(1)
	v_cmp_ne_u32_e32 vcc, 0, v2
	s_cbranch_vccnz .LBB0_1044
	v_readlane_b32 s2, v254, 0
	v_readlane_b32 s3, v254, 1
	s_load_dwordx2 s[0:1], s[2:3], 0x4
	s_add_u32 s2, s34, 0x1000
	s_addc_u32 s3, s35, 0
	s_add_u32 s6, s34, 0x1100
	s_addc_u32 s7, s35, 0
	s_add_u32 s8, s34, 0x1200
	s_addc_u32 s9, s35, 0
	s_add_u32 s10, s34, 0x1300
	s_waitcnt lgkmcnt(0)
	s_mul_i32 s20, s0, s96
	s_addc_u32 s11, s35, 0
	s_mul_i32 s20, s20, s1
	s_mov_b32 s21, 1
	s_mov_b64 s[0:1], 0
	v_mov_b64_e32 v[0:1], s[34:35]
	v_mov_b64_e32 v[2:3], s[2:3]
	v_mov_b64_e32 v[4:5], s[6:7]
	v_mov_b64_e32 v[6:7], s[8:9]
	v_mov_b64_e32 v[8:9], s[10:11]
	s_branch .LBB0_1034

; __device__ __forceinline__ unsigned xb_ld(unsigned* p)              { return __hip_atomic_load(p, __ATOMIC_RELAXED, __HIP_MEMORY_SCOPE_AGENT); }
; #define XB_SPIN(cond, bar) do { unsigned _sp = 0; while (cond) { __builtin_amdgcn_s_sleep(1); \
;     if ((++_sp & 255u) == 0u) { if (xb_ld(&(bar)[XB_TMO])) break; if (_sp > XB_SPIN_CAP) { atomicAdd(&(bar)[XB_TMO], 1u); break; } } } } while (0)
; __device__ __forceinline__ void xcd_barrier(const XcdBarrier& b) {
;     ...
;         XB_SPIN(xb_ld(&bar[XB_XGEN(b.x)]) == gen, bar);
;         __builtin_amdgcn_fence(__ATOMIC_ACQUIRE, "agent");
;         asm volatile("s_waitcnt vmcnt(0)" ::: "memory");
;     }
;     __syncthreads();
.LBB0_1058:
	s_or_b64 exec, exec, s[0:1]
	s_waitcnt vmcnt(0) lgkmcnt(0)
	s_waitcnt vmcnt(0)

; __device__ __forceinline__ unsigned xb_add(unsigned* p, unsigned v) { return __hip_atomic_fetch_add(p, v, __ATOMIC_RELAXED, __HIP_MEMORY_SCOPE_AGENT); }
; __device__ __forceinline__ void xcd_barrier(const XcdBarrier& b) {
;     asm volatile("s_waitcnt vmcnt(0)" ::: "memory");
;     __syncthreads();
;     const unsigned long long bp_ = (unsigned long long)b.bar; unsigned blo_ = __builtin_amdgcn_readfirstlane((unsigned)bp_), bhi_ = __builtin_amdgcn_readfirstlane((unsigned)(bp_ >> 32));
;     asm volatile("" : "+s"(blo_), "+s"(bhi_)); unsigned* bar = (unsigned*)(((unsigned long long)bhi_ << 32) | blo_);
;     if (threadIdx.x == 0) {
;         __builtin_amdgcn_s_waitcnt(0);
;         unsigned nloc = b.st[0], nx = b.st[1];
;         if (nloc == 0u) { xcd_barrier_complete(bar, b.x, nloc, nx); b.st[0] = nloc; b.st[1] = nx; }
;         const unsigned old = xb_add(&bar[XB_XSUB(b.x)], 1u);
;         const unsigned gen = old / nloc;
;         if (old + 1u == (gen + 1u) * nloc) {
.LBB0_1066:
	s_or_b64 exec, exec, s[0:1]
	v_mov_b32_e32 v0, 0x22600
	ds_read2_b32 v[0:1], v0 offset0:70 offset1:71
	v_mov_b32_e32 v2, 0x22568
	ds_read_b32 v2, v2
	s_waitcnt vmcnt(0)
	s_waitcnt lgkmcnt(0)
	v_readfirstlane_b32 s0, v0
	v_readfirstlane_b32 s1, v1
	s_add_u32 s34, s0, 0x4000
	v_readfirstlane_b32 s33, v2
	s_addc_u32 s35, s1, 0
	s_barrier
	s_mov_b64 s[4:5], exec
	v_readlane_b32 s0, v254, 3
	v_readlane_b32 s1, v254, 4
	s_and_b64 s[0:1], s[4:5], s[0:1]
	s_mov_b64 exec, s[0:1]
	s_cbranch_execz .LBB0_1096
	v_mov_b32_e32 v0, 0x22560
	s_waitcnt vmcnt(0) expcnt(0) lgkmcnt(0)
	buffer_inv sc1
	ds_read_b32 v2, v0
	v_mov_b32_e32 v0, 0x22564
	ds_read_b32 v0, v0
	s_waitcnt lgkmcnt(1)
	v_cmp_ne_u32_e32 vcc, 0, v2
	s_cbranch_vccnz .LBB0_1081
	v_readlane_b32 s2, v254, 0
	v_readlane_b32 s3, v254, 1
	s_load_dwordx2 s[0:1], s[2:3], 0x4
	s_add_u32 s2, s34, 0x1000
	s_addc_u32 s3, s35, 0
	s_add_u32 s6, s34, 0x1100
	s_addc_u32 s7, s35, 0
	s_add_u32 s8, s34, 0x1200
	s_addc_u32 s9, s35, 0
	s_add_u32 s10, s34, 0x1300
	s_waitcnt lgkmcnt(0)
	s_mul_i32 s20, s0, s96
	s_addc_u32 s11, s35, 0
	s_mul_i32 s20, s20, s1
	s_mov_b32 s21, 1
	s_mov_b64 s[0:1], 0
	v_mov_b64_e32 v[0:1], s[34:35]
	v_mov_b64_e32 v[2:3], s[2:3]
	v_mov_b64_e32 v[4:5], s[6:7]
	v_mov_b64_e32 v[6:7], s[8:9]
	v_mov_b64_e32 v[8:9], s[10:11]
	s_branch .LBB0_1071

; __device__ __forceinline__ unsigned xb_add(unsigned* p, unsigned v) { return __hip_atomic_fetch_add(p, v, __ATOMIC_RELAXED, __HIP_MEMORY_SCOPE_AGENT); }
; __device__ __forceinline__ void xcd_barrier(const XcdBarrier& b) {
;     asm volatile("s_waitcnt vmcnt(0)" ::: "memory");
;     __syncthreads();
;     const unsigned long long bp_ = (unsigned long long)b.bar; unsigned blo_ = __builtin_amdgcn_readfirstlane((unsigned)bp_), bhi_ = __builtin_amdgcn_readfirstlane((unsigned)(bp_ >> 32));
;     asm volatile("" : "+s"(blo_), "+s"(bhi_)); unsigned* bar = (unsigned*)(((unsigned long long)bhi_ << 32) | blo_);
;     if (threadIdx.x == 0) {
;         __builtin_amdgcn_s_waitcnt(0);
;         unsigned nloc = b.st[0], nx = b.st[1];
;         if (nloc == 0u) { xcd_barrier_complete(bar, b.x, nloc, nx); b.st[0] = nloc; b.st[1] = nx; }
;         const unsigned old = xb_add(&bar[XB_XSUB(b.x)], 1u);
;         const unsigned gen = old / nloc;
;         if (old + 1u == (gen + 1u) * nloc) {
.LBB0_1296:
	v_mov_b32_e32 v0, 0x22600
	s_waitcnt vmcnt(0)
	ds_read2_b32 v[2:3], v0 offset0:70 offset1:71
	ds_read_b32 v0, v250
	s_waitcnt vmcnt(0)
	s_waitcnt lgkmcnt(0)
	s_barrier
	v_readfirstlane_b32 s0, v2
	v_readfirstlane_b32 s1, v3
	s_add_u32 s34, s0, 0x4000
	s_addc_u32 s35, s1, 0
	v_readfirstlane_b32 s5, v0
	s_mov_b64 s[36:37], exec
	v_readlane_b32 s0, v254, 3
	v_readlane_b32 s1, v254, 4
	s_and_b64 s[0:1], s[36:37], s[0:1]
	s_mov_b64 exec, s[0:1]
	s_cbranch_execz .LBB0_1326
	s_waitcnt vmcnt(0) expcnt(0) lgkmcnt(0)
	buffer_inv sc1
	ds_read_b32 v2, v252
	ds_read_b32 v0, v253
	s_waitcnt lgkmcnt(1)
	v_cmp_ne_u32_e32 vcc, 0, v2
	s_cbranch_vccnz .LBB0_1311
	v_readlane_b32 s0, v254, 0
	v_readlane_b32 s1, v254, 1
	s_load_dwordx2 s[6:7], s[0:1], 0x4
	s_add_u32 s0, s34, 0x1000
	s_addc_u32 s1, s35, 0
	s_add_u32 s2, s34, 0x1100
	s_addc_u32 s3, s35, 0
	s_waitcnt lgkmcnt(0)
	s_mul_i32 s28, s6, s96
	s_add_u32 s6, s34, 0x1200
	s_mul_i32 s28, s28, s7
	s_addc_u32 s7, s35, 0
	s_add_u32 s8, s34, 0x1300
	s_addc_u32 s9, s35, 0
	s_mov_b32 s29, 1
	s_mov_b64 s[10:11], 0
	s_branch .LBB0_1301

; __device__ __forceinline__ unsigned xb_add(unsigned* p, unsigned v) { return __hip_atomic_fetch_add(p, v, __ATOMIC_RELAXED, __HIP_MEMORY_SCOPE_AGENT); }
; __device__ __forceinline__ void xcd_barrier(const XcdBarrier& b) {
;     asm volatile("s_waitcnt vmcnt(0)" ::: "memory");
;     __syncthreads();
;     const unsigned long long bp_ = (unsigned long long)b.bar; unsigned blo_ = __builtin_amdgcn_readfirstlane((unsigned)bp_), bhi_ = __builtin_amdgcn_readfirstlane((unsigned)(bp_ >> 32));
;     asm volatile("" : "+s"(blo_), "+s"(bhi_)); unsigned* bar = (unsigned*)(((unsigned long long)bhi_ << 32) | blo_);
;     if (threadIdx.x == 0) {
;         __builtin_amdgcn_s_waitcnt(0);
;         unsigned nloc = b.st[0], nx = b.st[1];
;         if (nloc == 0u) { xcd_barrier_complete(bar, b.x, nloc, nx); b.st[0] = nloc; b.st[1] = nx; }
;         const unsigned old = xb_add(&bar[XB_XSUB(b.x)], 1u);
;         const unsigned gen = old / nloc;
;         if (old + 1u == (gen + 1u) * nloc) {
.LBB0_1383:
	v_mov_b32_e32 v0, 0x22600
	ds_read2_b32 v[2:3], v0 offset0:70 offset1:71
	ds_read_b32 v0, v250
	s_waitcnt vmcnt(0)
	s_waitcnt lgkmcnt(0)
	s_barrier
	v_readfirstlane_b32 s0, v2
	v_readfirstlane_b32 s1, v3
	s_add_u32 s34, s0, 0x4000
	s_addc_u32 s35, s1, 0
	v_readfirstlane_b32 s5, v0
	s_mov_b64 s[36:37], exec
	v_readlane_b32 s0, v254, 3
	v_readlane_b32 s1, v254, 4
	s_and_b64 s[0:1], s[36:37], s[0:1]
	s_mov_b64 exec, s[0:1]
	s_cbranch_execz .LBB0_1413
	s_waitcnt vmcnt(0) expcnt(0) lgkmcnt(0)
	buffer_inv sc1
	ds_read_b32 v2, v252
	ds_read_b32 v0, v253
	s_waitcnt lgkmcnt(1)
	v_cmp_ne_u32_e32 vcc, 0, v2
	s_cbranch_vccnz .LBB0_1398
	v_readlane_b32 s0, v254, 0
	v_readlane_b32 s1, v254, 1
	s_load_dwordx2 s[6:7], s[0:1], 0x4
	s_add_u32 s0, s34, 0x1000
	s_addc_u32 s1, s35, 0
	s_add_u32 s2, s34, 0x1100
	s_addc_u32 s3, s35, 0
	s_waitcnt lgkmcnt(0)
	s_mul_i32 s28, s6, s96
	s_add_u32 s6, s34, 0x1200
	s_mul_i32 s28, s28, s7
	s_addc_u32 s7, s35, 0
	s_add_u32 s8, s34, 0x1300
	s_addc_u32 s9, s35, 0
	s_mov_b32 s29, 1
	s_mov_b64 s[10:11], 0
	s_branch .LBB0_1388

; #define GAS __attribute__((address_space(1)))
; __device__ __forceinline__ bf16 f2bf(float f) { return (bf16)(cvt_pk_bf16(f, 0.f) & 0xffffu); }
; __device__ __forceinline__ float ex2(float x) { return __builtin_amdgcn_exp2f(x); }
; __device__ __forceinline__ GAS unsigned char* wsp(const Ctx& c) { return (GAS unsigned char*)ptab(c, 35); }
; __device__ __forceinline__ void ret_scan_phase(const Ctx& c0) { const Ctx c = fresh(c0);
;     const GAS float* KVT = (const GAS float*)(wsp(c) + WS_KVT); GAS bf16* PV = (GAS bf16*)(wsp(c) + WS_PREVT);
;     for (int e = c.bx * 512 + c.tid; e < 8 * 16384; e += c.G * 512) { const int h = e >> 14;
;         const float lg = l2gamma(h), g1 = ex2(lg), g127 = ex2(127.f * lg), g128 = ex2(128.f * lg);
;         const int off = (h << 14) + (e & 16383); float st = 0.f;
;         for (int n0 = 0; n0 < 64; n0 += 8) { float kv[8];
; #pragma unroll
;             for (int q = 0; q < 8; ++q) kv[q] = KVT[(size_t)(n0 + q) * 8 * 16384 + off];
; #pragma unroll
;             for (int q = 0; q < 8; ++q) { PV[(size_t)(n0 + q) * 8 * 16384 + off] = f2bf(g1 * st); st = g128 * st + g127 * kv[q]; } } }
; }
.LBB0_1424:
	s_or_b64 exec, exec, s[8:9]
	v_exp_f32_e32 v0, v8
	v_mul_f32_e32 v3, 0x42fe0000, v8
	v_exp_f32_e32 v3, v3
	v_mul_f32_e32 v8, 0x43000000, v8
	v_exp_f32_e32 v8, v8
	v_mov_b32_e32 v9, 0x22600
	ds_read2_b32 v[10:11], v9 offset0:70 offset1:71
	v_lshlrev_b32_e32 v20, 2, v2
	v_lshlrev_b32_e32 v21, 1, v2
	v_mov_b32_e32 v9, 0
	s_waitcnt lgkmcnt(0)
	v_readfirstlane_b32 s10, v10
	v_readfirstlane_b32 s11, v11
	s_nop 3
	s_add_u32 s12, s10, 0x4a900000
	s_addc_u32 s13, s11, 0
	s_add_u32 s10, s10, 0x48900000
	s_addc_u32 s11, s11, 0
	global_load_dword v30, v20, s[10:11]
	s_add_u32 s10, s10, 0x80000
	s_addc_u32 s11, s11, 0
	global_load_dword v31, v20, s[10:11]
	s_add_u32 s10, s10, 0x80000
	s_addc_u32 s11, s11, 0
	global_load_dword v32, v20, s[10:11]
	s_add_u32 s10, s10, 0x80000
	s_addc_u32 s11, s11, 0
	global_load_dword v33, v20, s[10:11]
	s_add_u32 s10, s10, 0x80000
	s_addc_u32 s11, s11, 0
	global_load_dword v34, v20, s[10:11]
	s_add_u32 s10, s10, 0x80000
	s_addc_u32 s11, s11, 0
	global_load_dword v35, v20, s[10:11]
	s_add_u32 s10, s10, 0x80000
	s_addc_u32 s11, s11, 0
	global_load_dword v36, v20, s[10:11]
	s_add_u32 s10, s10, 0x80000
	s_addc_u32 s11, s11, 0
	global_load_dword v37, v20, s[10:11]
	s_add_u32 s10, s10, 0x80000
	s_addc_u32 s11, s11, 0
	global_load_dword v38, v20, s[10:11]
	s_add_u32 s10, s10, 0x80000
	s_addc_u32 s11, s11, 0
	global_load_dword v39, v20, s[10:11]
	s_add_u32 s10, s10, 0x80000
	s_addc_u32 s11, s11, 0
	global_load_dword v40, v20, s[10:11]
	s_add_u32 s10, s10, 0x80000
	s_addc_u32 s11, s11, 0
	global_load_dword v41, v20, s[10:11]
	s_add_u32 s10, s10, 0x80000
	s_addc_u32 s11, s11, 0
	global_load_dword v42, v20, s[10:11]
	s_add_u32 s10, s10, 0x80000
	s_addc_u32 s11, s11, 0
	global_load_dword v43, v20, s[10:11]
	s_add_u32 s10, s10, 0x80000
	s_addc_u32 s11, s11, 0
	global_load_dword v44, v20, s[10:11]
	s_add_u32 s10, s10, 0x80000
	s_addc_u32 s11, s11, 0
	global_load_dword v45, v20, s[10:11]
	s_add_u32 s10, s10, 0x80000
	s_addc_u32 s11, s11, 0
	global_load_dword v46, v20, s[10:11]
	s_add_u32 s10, s10, 0x80000
	s_addc_u32 s11, s11, 0
	global_load_dword v47, v20, s[10:11]
	s_add_u32 s10, s10, 0x80000
	s_addc_u32 s11, s11, 0
	global_load_dword v48, v20, s[10:11]
	s_add_u32 s10, s10, 0x80000
	s_addc_u32 s11, s11, 0
	global_load_dword v49, v20, s[10:11]
	s_add_u32 s10, s10, 0x80000
	s_addc_u32 s11, s11, 0
	global_load_dword v50, v20, s[10:11]
	s_add_u32 s10, s10, 0x80000
	s_addc_u32 s11, s11, 0
	global_load_dword v51, v20, s[10:11]
	s_add_u32 s10, s10, 0x80000
	s_addc_u32 s11, s11, 0
	global_load_dword v52, v20, s[10:11]
	s_add_u32 s10, s10, 0x80000
	s_addc_u32 s11, s11, 0
	global_load_dword v53, v20, s[10:11]
	s_add_u32 s10, s10, 0x80000
	s_addc_u32 s11, s11, 0
	global_load_dword v54, v20, s[10:11]
	s_add_u32 s10, s10, 0x80000
	s_addc_u32 s11, s11, 0
	global_load_dword v55, v20, s[10:11]
	s_add_u32 s10, s10, 0x80000
	s_addc_u32 s11, s11, 0
	global_load_dword v56, v20, s[10:11]
	s_add_u32 s10, s10, 0x80000
	s_addc_u32 s11, s11, 0
	global_load_dword v57, v20, s[10:11]
	s_add_u32 s10, s10, 0x80000
	s_addc_u32 s11, s11, 0
	global_load_dword v58, v20, s[10:11]
	s_add_u32 s10, s10, 0x80000
	s_addc_u32 s11, s11, 0
	global_load_dword v59, v20, s[10:11]
	s_add_u32 s10, s10, 0x80000
	s_addc_u32 s11, s11, 0
	global_load_dword v60, v20, s[10:11]
	s_add_u32 s10, s10, 0x80000
	s_addc_u32 s11, s11, 0
	global_load_dword v61, v20, s[10:11]
	s_add_u32 s10, s10, 0x80000
	s_addc_u32 s11, s11, 0
	v_mul_f32_e32 v10, v0, v9
	v_cvt_pk_bf16_f32 v10, v10, v10
	global_store_short v21, v10, s[12:13]
	s_add_u32 s12, s12, 0x40000
	s_addc_u32 s13, s13, 0
	v_mul_f32_e32 v9, v8, v9
	s_waitcnt vmcnt(32)
	v_fmac_f32_e32 v9, v3, v30
	v_mul_f32_e32 v11, v0, v9
	v_cvt_pk_bf16_f32 v11, v11, v11
	global_store_short v21, v11, s[12:13]
	s_add_u32 s12, s12, 0x40000
	s_addc_u32 s13, s13, 0
	v_mul_f32_e32 v9, v8, v9
	s_waitcnt vmcnt(32)
	v_fmac_f32_e32 v9, v3, v31
	v_mul_f32_e32 v10, v0, v9
	v_cvt_pk_bf16_f32 v10, v10, v10
	global_store_short v21, v10, s[12:13]
	s_add_u32 s12, s12, 0x40000
	s_addc_u32 s13, s13, 0
	v_mul_f32_e32 v9, v8, v9
	s_waitcnt vmcnt(32)
	v_fmac_f32_e32 v9, v3, v32
	v_mul_f32_e32 v11, v0, v9
	v_cvt_pk_bf16_f32 v11, v11, v11
	global_store_short v21, v11, s[12:13]
	s_add_u32 s12, s12, 0x40000
	s_addc_u32 s13, s13, 0
	v_mul_f32_e32 v9, v8, v9
	s_waitcnt vmcnt(32)
	v_fmac_f32_e32 v9, v3, v33
	v_mul_f32_e32 v10, v0, v9
	v_cvt_pk_bf16_f32 v10, v10, v10
	global_store_short v21, v10, s[12:13]
	s_add_u32 s12, s12, 0x40000
	s_addc_u32 s13, s13, 0
	v_mul_f32_e32 v9, v8, v9
	s_waitcnt vmcnt(32)
	v_fmac_f32_e32 v9, v3, v34
	v_mul_f32_e32 v11, v0, v9
	v_cvt_pk_bf16_f32 v11, v11, v11
	global_store_short v21, v11, s[12:13]
	s_add_u32 s12, s12, 0x40000
	s_addc_u32 s13, s13, 0
	v_mul_f32_e32 v9, v8, v9
	s_waitcnt vmcnt(32)
	v_fmac_f32_e32 v9, v3, v35
	v_mul_f32_e32 v10, v0, v9
	v_cvt_pk_bf16_f32 v10, v10, v10
	global_store_short v21, v10, s[12:13]
	s_add_u32 s12, s12, 0x40000
	s_addc_u32 s13, s13, 0
	v_mul_f32_e32 v9, v8, v9
	s_waitcnt vmcnt(32)
	v_fmac_f32_e32 v9, v3, v36
	v_mul_f32_e32 v11, v0, v9
	v_cvt_pk_bf16_f32 v11, v11, v11
	global_store_short v21, v11, s[12:13]
	s_add_u32 s12, s12, 0x40000
	s_addc_u32 s13, s13, 0
	v_mul_f32_e32 v9, v8, v9
	s_waitcnt vmcnt(32)
; __device__ __forceinline__ bf16 f2bf(float f) { return (bf16)(cvt_pk_bf16(f, 0.f) & 0xffffu); }
; __device__ __forceinline__ float ex2(float x) { return __builtin_amdgcn_exp2f(x); }
; __device__ __forceinline__ void ret_scan_phase(const Ctx& c0) { const Ctx c = fresh(c0);
;     ...
;         const float lg = l2gamma(h), g1 = ex2(lg), g127 = ex2(127.f * lg), g128 = ex2(128.f * lg);
;         const int off = (h << 14) + (e & 16383); float st = 0.f;
;         for (int n0 = 0; n0 < 64; n0 += 8) { float kv[8];
; #pragma unroll
;             for (int q = 0; q < 8; ++q) kv[q] = KVT[(size_t)(n0 + q) * 8 * 16384 + off];
; #pragma unroll
;             for (int q = 0; q < 8; ++q) { PV[(size_t)(n0 + q) * 8 * 16384 + off] = f2bf(g1 * st); st = g128 * st + g127 * kv[q]; } } }
; }
	v_fmac_f32_e32 v9, v3, v37
	global_load_dword v30, v20, s[10:11]
	s_add_u32 s10, s10, 0x80000
	s_addc_u32 s11, s11, 0
	global_load_dword v31, v20, s[10:11]
	s_add_u32 s10, s10, 0x80000
	s_addc_u32 s11, s11, 0
	global_load_dword v32, v20, s[10:11]
	s_add_u32 s10, s10, 0x80000
	s_addc_u32 s11, s11, 0
	global_load_dword v33, v20, s[10:11]
	s_add_u32 s10, s10, 0x80000
	s_addc_u32 s11, s11, 0
	global_load_dword v34, v20, s[10:11]
	s_add_u32 s10, s10, 0x80000
	s_addc_u32 s11, s11, 0
	global_load_dword v35, v20, s[10:11]
	s_add_u32 s10, s10, 0x80000
	s_addc_u32 s11, s11, 0
	global_load_dword v36, v20, s[10:11]
	s_add_u32 s10, s10, 0x80000
	s_addc_u32 s11, s11, 0
	global_load_dword v37, v20, s[10:11]
	s_add_u32 s10, s10, 0x80000
	s_addc_u32 s11, s11, 0
	v_mul_f32_e32 v10, v0, v9
	v_cvt_pk_bf16_f32 v10, v10, v10
	global_store_short v21, v10, s[12:13]
	s_add_u32 s12, s12, 0x40000
	s_addc_u32 s13, s13, 0
	v_mul_f32_e32 v9, v8, v9
	s_waitcnt vmcnt(40)
	v_fmac_f32_e32 v9, v3, v38
	v_mul_f32_e32 v11, v0, v9
	v_cvt_pk_bf16_f32 v11, v11, v11
	global_store_short v21, v11, s[12:13]
	s_add_u32 s12, s12, 0x40000
	s_addc_u32 s13, s13, 0
	v_mul_f32_e32 v9, v8, v9
	s_waitcnt vmcnt(40)
	v_fmac_f32_e32 v9, v3, v39
	v_mul_f32_e32 v10, v0, v9
	v_cvt_pk_bf16_f32 v10, v10, v10
	global_store_short v21, v10, s[12:13]
	s_add_u32 s12, s12, 0x40000
	s_addc_u32 s13, s13, 0
	v_mul_f32_e32 v9, v8, v9
	s_waitcnt vmcnt(40)
	v_fmac_f32_e32 v9, v3, v40
	v_mul_f32_e32 v11, v0, v9
	v_cvt_pk_bf16_f32 v11, v11, v11
	global_store_short v21, v11, s[12:13]
	s_add_u32 s12, s12, 0x40000
	s_addc_u32 s13, s13, 0
	v_mul_f32_e32 v9, v8, v9
	s_waitcnt vmcnt(40)
	v_fmac_f32_e32 v9, v3, v41
	v_mul_f32_e32 v10, v0, v9
	v_cvt_pk_bf16_f32 v10, v10, v10
	global_store_short v21, v10, s[12:13]
	s_add_u32 s12, s12, 0x40000
	s_addc_u32 s13, s13, 0
	v_mul_f32_e32 v9, v8, v9
	s_waitcnt vmcnt(40)
	v_fmac_f32_e32 v9, v3, v42
	v_mul_f32_e32 v11, v0, v9
	v_cvt_pk_bf16_f32 v11, v11, v11
	global_store_short v21, v11, s[12:13]
	s_add_u32 s12, s12, 0x40000
	s_addc_u32 s13, s13, 0
	v_mul_f32_e32 v9, v8, v9
	s_waitcnt vmcnt(40)
	v_fmac_f32_e32 v9, v3, v43
	v_mul_f32_e32 v10, v0, v9
	v_cvt_pk_bf16_f32 v10, v10, v10
	global_store_short v21, v10, s[12:13]
	s_add_u32 s12, s12, 0x40000
	s_addc_u32 s13, s13, 0
	v_mul_f32_e32 v9, v8, v9
	s_waitcnt vmcnt(40)
	v_fmac_f32_e32 v9, v3, v44
	v_mul_f32_e32 v11, v0, v9
	v_cvt_pk_bf16_f32 v11, v11, v11
	global_store_short v21, v11, s[12:13]
	s_add_u32 s12, s12, 0x40000
	s_addc_u32 s13, s13, 0
	v_mul_f32_e32 v9, v8, v9
	s_waitcnt vmcnt(40)
	v_fmac_f32_e32 v9, v3, v45
	global_load_dword v38, v20, s[10:11]
	s_add_u32 s10, s10, 0x80000
	s_addc_u32 s11, s11, 0
	global_load_dword v39, v20, s[10:11]
	s_add_u32 s10, s10, 0x80000
	s_addc_u32 s11, s11, 0
	global_load_dword v40, v20, s[10:11]
	s_add_u32 s10, s10, 0x80000
	s_addc_u32 s11, s11, 0
	global_load_dword v41, v20, s[10:11]
	s_add_u32 s10, s10, 0x80000
	s_addc_u32 s11, s11, 0
	global_load_dword v42, v20, s[10:11]
	s_add_u32 s10, s10, 0x80000
	s_addc_u32 s11, s11, 0
	global_load_dword v43, v20, s[10:11]
	s_add_u32 s10, s10, 0x80000
	s_addc_u32 s11, s11, 0
	global_load_dword v44, v20, s[10:11]
	s_add_u32 s10, s10, 0x80000
	s_addc_u32 s11, s11, 0
	global_load_dword v45, v20, s[10:11]
	s_add_u32 s10, s10, 0x80000
	s_addc_u32 s11, s11, 0
	v_mul_f32_e32 v10, v0, v9
	v_cvt_pk_bf16_f32 v10, v10, v10
	global_store_short v21, v10, s[12:13]
	s_add_u32 s12, s12, 0x40000
	s_addc_u32 s13, s13, 0
	v_mul_f32_e32 v9, v8, v9
	s_waitcnt vmcnt(48)
	v_fmac_f32_e32 v9, v3, v46
	v_mul_f32_e32 v11, v0, v9
	v_cvt_pk_bf16_f32 v11, v11, v11
	global_store_short v21, v11, s[12:13]
	s_add_u32 s12, s12, 0x40000
	s_addc_u32 s13, s13, 0
	v_mul_f32_e32 v9, v8, v9
	s_waitcnt vmcnt(48)
	v_fmac_f32_e32 v9, v3, v47
	v_mul_f32_e32 v10, v0, v9
	v_cvt_pk_bf16_f32 v10, v10, v10
	global_store_short v21, v10, s[12:13]
	s_add_u32 s12, s12, 0x40000
	s_addc_u32 s13, s13, 0
	v_mul_f32_e32 v9, v8, v9
	s_waitcnt vmcnt(48)
	v_fmac_f32_e32 v9, v3, v48
	v_mul_f32_e32 v11, v0, v9
	v_cvt_pk_bf16_f32 v11, v11, v11
	global_store_short v21, v11, s[12:13]
	s_add_u32 s12, s12, 0x40000
	s_addc_u32 s13, s13, 0
	v_mul_f32_e32 v9, v8, v9
	s_waitcnt vmcnt(48)
	v_fmac_f32_e32 v9, v3, v49
	v_mul_f32_e32 v10, v0, v9
	v_cvt_pk_bf16_f32 v10, v10, v10
	global_store_short v21, v10, s[12:13]
	s_add_u32 s12, s12, 0x40000
	s_addc_u32 s13, s13, 0
	v_mul_f32_e32 v9, v8, v9
	s_waitcnt vmcnt(48)
	v_fmac_f32_e32 v9, v3, v50
	v_mul_f32_e32 v11, v0, v9
	v_cvt_pk_bf16_f32 v11, v11, v11
	global_store_short v21, v11, s[12:13]
	s_add_u32 s12, s12, 0x40000
	s_addc_u32 s13, s13, 0
	v_mul_f32_e32 v9, v8, v9
	s_waitcnt vmcnt(48)
	v_fmac_f32_e32 v9, v3, v51
	v_mul_f32_e32 v10, v0, v9
	v_cvt_pk_bf16_f32 v10, v10, v10
	global_store_short v21, v10, s[12:13]
	s_add_u32 s12, s12, 0x40000
	s_addc_u32 s13, s13, 0
	v_mul_f32_e32 v9, v8, v9
	s_waitcnt vmcnt(48)
	v_fmac_f32_e32 v9, v3, v52
	v_mul_f32_e32 v11, v0, v9
	v_cvt_pk_bf16_f32 v11, v11, v11
	global_store_short v21, v11, s[12:13]
	s_add_u32 s12, s12, 0x40000
	s_addc_u32 s13, s13, 0
	v_mul_f32_e32 v9, v8, v9
	s_waitcnt vmcnt(48)
	v_fmac_f32_e32 v9, v3, v53
	global_load_dword v46, v20, s[10:11]
	s_add_u32 s10, s10, 0x80000
	s_addc_u32 s11, s11, 0
	global_load_dword v47, v20, s[10:11]
	s_add_u32 s10, s10, 0x80000
	s_addc_u32 s11, s11, 0
	global_load_dword v48, v20, s[10:11]
	s_add_u32 s10, s10, 0x80000
	s_addc_u32 s11, s11, 0
	global_load_dword v49, v20, s[10:11]
	s_add_u32 s10, s10, 0x80000
	s_addc_u32 s11, s11, 0
	global_load_dword v50, v20, s[10:11]
	s_add_u32 s10, s10, 0x80000
	s_addc_u32 s11, s11, 0
	global_load_dword v51, v20, s[10:11]
	s_add_u32 s10, s10, 0x80000
	s_addc_u32 s11, s11, 0
	global_load_dword v52, v20, s[10:11]
	s_add_u32 s10, s10, 0x80000
	s_addc_u32 s11, s11, 0
	global_load_dword v53, v20, s[10:11]
	s_add_u32 s10, s10, 0x80000
	s_addc_u32 s11, s11, 0
	v_mul_f32_e32 v10, v0, v9
	v_cvt_pk_bf16_f32 v10, v10, v10
	global_store_short v21, v10, s[12:13]
	s_add_u32 s12, s12, 0x40000
	s_addc_u32 s13, s13, 0
	v_mul_f32_e32 v9, v8, v9
	s_waitcnt vmcnt(56)
; __device__ __forceinline__ bf16 f2bf(float f) { return (bf16)(cvt_pk_bf16(f, 0.f) & 0xffffu); }
; __device__ __forceinline__ float ex2(float x) { return __builtin_amdgcn_exp2f(x); }
; __device__ __forceinline__ void ret_scan_phase(const Ctx& c0) { const Ctx c = fresh(c0);
;     ...
;         const float lg = l2gamma(h), g1 = ex2(lg), g127 = ex2(127.f * lg), g128 = ex2(128.f * lg);
;         const int off = (h << 14) + (e & 16383); float st = 0.f;
;         for (int n0 = 0; n0 < 64; n0 += 8) { float kv[8];
; #pragma unroll
;             for (int q = 0; q < 8; ++q) kv[q] = KVT[(size_t)(n0 + q) * 8 * 16384 + off];
; #pragma unroll
;             for (int q = 0; q < 8; ++q) { PV[(size_t)(n0 + q) * 8 * 16384 + off] = f2bf(g1 * st); st = g128 * st + g127 * kv[q]; } } }
; }
	v_fmac_f32_e32 v9, v3, v54
	v_mul_f32_e32 v11, v0, v9
	v_cvt_pk_bf16_f32 v11, v11, v11
	global_store_short v21, v11, s[12:13]
	s_add_u32 s12, s12, 0x40000
	s_addc_u32 s13, s13, 0
	v_mul_f32_e32 v9, v8, v9
	s_waitcnt vmcnt(56)
	v_fmac_f32_e32 v9, v3, v55
	v_mul_f32_e32 v10, v0, v9
	v_cvt_pk_bf16_f32 v10, v10, v10
	global_store_short v21, v10, s[12:13]
	s_add_u32 s12, s12, 0x40000
	s_addc_u32 s13, s13, 0
	v_mul_f32_e32 v9, v8, v9
	s_waitcnt vmcnt(56)
	v_fmac_f32_e32 v9, v3, v56
	v_mul_f32_e32 v11, v0, v9
	v_cvt_pk_bf16_f32 v11, v11, v11
	global_store_short v21, v11, s[12:13]
	s_add_u32 s12, s12, 0x40000
	s_addc_u32 s13, s13, 0
	v_mul_f32_e32 v9, v8, v9
	s_waitcnt vmcnt(56)
	v_fmac_f32_e32 v9, v3, v57
	v_mul_f32_e32 v10, v0, v9
	v_cvt_pk_bf16_f32 v10, v10, v10
	global_store_short v21, v10, s[12:13]
	s_add_u32 s12, s12, 0x40000
	s_addc_u32 s13, s13, 0
	v_mul_f32_e32 v9, v8, v9
	s_waitcnt vmcnt(56)
	v_fmac_f32_e32 v9, v3, v58
	v_mul_f32_e32 v11, v0, v9
	v_cvt_pk_bf16_f32 v11, v11, v11
	global_store_short v21, v11, s[12:13]
	s_add_u32 s12, s12, 0x40000
	s_addc_u32 s13, s13, 0
	v_mul_f32_e32 v9, v8, v9
	s_waitcnt vmcnt(56)
	v_fmac_f32_e32 v9, v3, v59
	v_mul_f32_e32 v10, v0, v9
	v_cvt_pk_bf16_f32 v10, v10, v10
	global_store_short v21, v10, s[12:13]
	s_add_u32 s12, s12, 0x40000
	s_addc_u32 s13, s13, 0
	v_mul_f32_e32 v9, v8, v9
	s_waitcnt vmcnt(56)
	v_fmac_f32_e32 v9, v3, v60
	v_mul_f32_e32 v11, v0, v9
	v_cvt_pk_bf16_f32 v11, v11, v11
	global_store_short v21, v11, s[12:13]
	s_add_u32 s12, s12, 0x40000
	s_addc_u32 s13, s13, 0
	v_mul_f32_e32 v9, v8, v9
	s_waitcnt vmcnt(56)
	v_fmac_f32_e32 v9, v3, v61
	global_load_dword v54, v20, s[10:11]
	s_add_u32 s10, s10, 0x80000
	s_addc_u32 s11, s11, 0
	global_load_dword v55, v20, s[10:11]
	s_add_u32 s10, s10, 0x80000
	s_addc_u32 s11, s11, 0
	global_load_dword v56, v20, s[10:11]
	s_add_u32 s10, s10, 0x80000
	s_addc_u32 s11, s11, 0
	global_load_dword v57, v20, s[10:11]
	s_add_u32 s10, s10, 0x80000
	s_addc_u32 s11, s11, 0
	global_load_dword v58, v20, s[10:11]
	s_add_u32 s10, s10, 0x80000
	s_addc_u32 s11, s11, 0
	global_load_dword v59, v20, s[10:11]
	s_add_u32 s10, s10, 0x80000
	s_addc_u32 s11, s11, 0
	global_load_dword v60, v20, s[10:11]
	s_add_u32 s10, s10, 0x80000
	s_addc_u32 s11, s11, 0
	global_load_dword v61, v20, s[10:11]
	s_add_u32 s10, s10, 0x80000
	s_addc_u32 s11, s11, 0
	v_mul_f32_e32 v10, v0, v9
	v_cvt_pk_bf16_f32 v10, v10, v10
	global_store_short v21, v10, s[12:13]
	s_add_u32 s12, s12, 0x40000
	s_addc_u32 s13, s13, 0
	v_mul_f32_e32 v9, v8, v9
	s_waitcnt vmcnt(56)
	v_fmac_f32_e32 v9, v3, v30
	v_mul_f32_e32 v11, v0, v9
	v_cvt_pk_bf16_f32 v11, v11, v11
	global_store_short v21, v11, s[12:13]
	s_add_u32 s12, s12, 0x40000
	s_addc_u32 s13, s13, 0
	v_mul_f32_e32 v9, v8, v9
	s_waitcnt vmcnt(56)
	v_fmac_f32_e32 v9, v3, v31
	v_mul_f32_e32 v10, v0, v9
	v_cvt_pk_bf16_f32 v10, v10, v10
	global_store_short v21, v10, s[12:13]
	s_add_u32 s12, s12, 0x40000
	s_addc_u32 s13, s13, 0
	v_mul_f32_e32 v9, v8, v9
	s_waitcnt vmcnt(56)
	v_fmac_f32_e32 v9, v3, v32
	v_mul_f32_e32 v11, v0, v9
	v_cvt_pk_bf16_f32 v11, v11, v11
	global_store_short v21, v11, s[12:13]
	s_add_u32 s12, s12, 0x40000
	s_addc_u32 s13, s13, 0
	v_mul_f32_e32 v9, v8, v9
	s_waitcnt vmcnt(56)
	v_fmac_f32_e32 v9, v3, v33
	v_mul_f32_e32 v10, v0, v9
	v_cvt_pk_bf16_f32 v10, v10, v10
	global_store_short v21, v10, s[12:13]
	s_add_u32 s12, s12, 0x40000
	s_addc_u32 s13, s13, 0
	v_mul_f32_e32 v9, v8, v9
	s_waitcnt vmcnt(56)
	v_fmac_f32_e32 v9, v3, v34
	v_mul_f32_e32 v11, v0, v9
	v_cvt_pk_bf16_f32 v11, v11, v11
	global_store_short v21, v11, s[12:13]
	s_add_u32 s12, s12, 0x40000
	s_addc_u32 s13, s13, 0
	v_mul_f32_e32 v9, v8, v9
	s_waitcnt vmcnt(56)
	v_fmac_f32_e32 v9, v3, v35
	v_mul_f32_e32 v10, v0, v9
	v_cvt_pk_bf16_f32 v10, v10, v10
	global_store_short v21, v10, s[12:13]
	s_add_u32 s12, s12, 0x40000
	s_addc_u32 s13, s13, 0
	v_mul_f32_e32 v9, v8, v9
	s_waitcnt vmcnt(56)
	v_fmac_f32_e32 v9, v3, v36
	v_mul_f32_e32 v11, v0, v9
	v_cvt_pk_bf16_f32 v11, v11, v11
	global_store_short v21, v11, s[12:13]
	s_add_u32 s12, s12, 0x40000
	s_addc_u32 s13, s13, 0
	v_mul_f32_e32 v9, v8, v9
	s_waitcnt vmcnt(56)
	v_fmac_f32_e32 v9, v3, v37
	v_mul_f32_e32 v10, v0, v9
	v_cvt_pk_bf16_f32 v10, v10, v10
	global_store_short v21, v10, s[12:13]
	s_add_u32 s12, s12, 0x40000
	s_addc_u32 s13, s13, 0
	v_mul_f32_e32 v9, v8, v9
	s_waitcnt vmcnt(48)
	v_fmac_f32_e32 v9, v3, v38
	v_mul_f32_e32 v11, v0, v9
	v_cvt_pk_bf16_f32 v11, v11, v11
	global_store_short v21, v11, s[12:13]
	s_add_u32 s12, s12, 0x40000
	s_addc_u32 s13, s13, 0
	v_mul_f32_e32 v9, v8, v9
	s_waitcnt vmcnt(48)
	v_fmac_f32_e32 v9, v3, v39
	v_mul_f32_e32 v10, v0, v9
	v_cvt_pk_bf16_f32 v10, v10, v10
	global_store_short v21, v10, s[12:13]
	s_add_u32 s12, s12, 0x40000
	s_addc_u32 s13, s13, 0
	v_mul_f32_e32 v9, v8, v9
	s_waitcnt vmcnt(48)
	v_fmac_f32_e32 v9, v3, v40
	v_mul_f32_e32 v11, v0, v9
	v_cvt_pk_bf16_f32 v11, v11, v11
	global_store_short v21, v11, s[12:13]
	s_add_u32 s12, s12, 0x40000
	s_addc_u32 s13, s13, 0
	v_mul_f32_e32 v9, v8, v9
	s_waitcnt vmcnt(48)
; __device__ __forceinline__ bf16 f2bf(float f) { return (bf16)(cvt_pk_bf16(f, 0.f) & 0xffffu); }
; __device__ __forceinline__ float ex2(float x) { return __builtin_amdgcn_exp2f(x); }
; __device__ __forceinline__ void ret_scan_phase(const Ctx& c0) { const Ctx c = fresh(c0);
;     ...
;         const float lg = l2gamma(h), g1 = ex2(lg), g127 = ex2(127.f * lg), g128 = ex2(128.f * lg);
;         const int off = (h << 14) + (e & 16383); float st = 0.f;
;         for (int n0 = 0; n0 < 64; n0 += 8) { float kv[8];
; #pragma unroll
;             for (int q = 0; q < 8; ++q) kv[q] = KVT[(size_t)(n0 + q) * 8 * 16384 + off];
; #pragma unroll
;             for (int q = 0; q < 8; ++q) { PV[(size_t)(n0 + q) * 8 * 16384 + off] = f2bf(g1 * st); st = g128 * st + g127 * kv[q]; } } }
; }
	v_fmac_f32_e32 v9, v3, v41
	v_mul_f32_e32 v10, v0, v9
	v_cvt_pk_bf16_f32 v10, v10, v10
	global_store_short v21, v10, s[12:13]
	s_add_u32 s12, s12, 0x40000
	s_addc_u32 s13, s13, 0
	v_mul_f32_e32 v9, v8, v9
	s_waitcnt vmcnt(48)
	v_fmac_f32_e32 v9, v3, v42
	v_mul_f32_e32 v11, v0, v9
	v_cvt_pk_bf16_f32 v11, v11, v11
	global_store_short v21, v11, s[12:13]
	s_add_u32 s12, s12, 0x40000
	s_addc_u32 s13, s13, 0
	v_mul_f32_e32 v9, v8, v9
	s_waitcnt vmcnt(48)
	v_fmac_f32_e32 v9, v3, v43
	v_mul_f32_e32 v10, v0, v9
	v_cvt_pk_bf16_f32 v10, v10, v10
	global_store_short v21, v10, s[12:13]
	s_add_u32 s12, s12, 0x40000
	s_addc_u32 s13, s13, 0
	v_mul_f32_e32 v9, v8, v9
	s_waitcnt vmcnt(48)
	v_fmac_f32_e32 v9, v3, v44
	v_mul_f32_e32 v11, v0, v9
	v_cvt_pk_bf16_f32 v11, v11, v11
	global_store_short v21, v11, s[12:13]
	s_add_u32 s12, s12, 0x40000
	s_addc_u32 s13, s13, 0
	v_mul_f32_e32 v9, v8, v9
	s_waitcnt vmcnt(48)
	v_fmac_f32_e32 v9, v3, v45
	v_mul_f32_e32 v10, v0, v9
	v_cvt_pk_bf16_f32 v10, v10, v10
	global_store_short v21, v10, s[12:13]
	s_add_u32 s12, s12, 0x40000
	s_addc_u32 s13, s13, 0
	v_mul_f32_e32 v9, v8, v9
	s_waitcnt vmcnt(40)
	v_fmac_f32_e32 v9, v3, v46
	v_mul_f32_e32 v11, v0, v9
	v_cvt_pk_bf16_f32 v11, v11, v11
	global_store_short v21, v11, s[12:13]
	s_add_u32 s12, s12, 0x40000
	s_addc_u32 s13, s13, 0
	v_mul_f32_e32 v9, v8, v9
	s_waitcnt vmcnt(40)
	v_fmac_f32_e32 v9, v3, v47
	v_mul_f32_e32 v10, v0, v9
	v_cvt_pk_bf16_f32 v10, v10, v10
	global_store_short v21, v10, s[12:13]
	s_add_u32 s12, s12, 0x40000
	s_addc_u32 s13, s13, 0
	v_mul_f32_e32 v9, v8, v9
	s_waitcnt vmcnt(40)
	v_fmac_f32_e32 v9, v3, v48
	v_mul_f32_e32 v11, v0, v9
	v_cvt_pk_bf16_f32 v11, v11, v11
	global_store_short v21, v11, s[12:13]
	s_add_u32 s12, s12, 0x40000
	s_addc_u32 s13, s13, 0
	v_mul_f32_e32 v9, v8, v9
	s_waitcnt vmcnt(40)
	v_fmac_f32_e32 v9, v3, v49
	v_mul_f32_e32 v10, v0, v9
	v_cvt_pk_bf16_f32 v10, v10, v10
	global_store_short v21, v10, s[12:13]
	s_add_u32 s12, s12, 0x40000
	s_addc_u32 s13, s13, 0
	v_mul_f32_e32 v9, v8, v9
	s_waitcnt vmcnt(40)
	v_fmac_f32_e32 v9, v3, v50
	v_mul_f32_e32 v11, v0, v9
	v_cvt_pk_bf16_f32 v11, v11, v11
	global_store_short v21, v11, s[12:13]
	s_add_u32 s12, s12, 0x40000
	s_addc_u32 s13, s13, 0
	v_mul_f32_e32 v9, v8, v9
	s_waitcnt vmcnt(40)
	v_fmac_f32_e32 v9, v3, v51
	v_mul_f32_e32 v10, v0, v9
	v_cvt_pk_bf16_f32 v10, v10, v10
	global_store_short v21, v10, s[12:13]
	s_add_u32 s12, s12, 0x40000
	s_addc_u32 s13, s13, 0
	v_mul_f32_e32 v9, v8, v9
	s_waitcnt vmcnt(40)
	v_fmac_f32_e32 v9, v3, v52
	v_mul_f32_e32 v11, v0, v9
	v_cvt_pk_bf16_f32 v11, v11, v11
	global_store_short v21, v11, s[12:13]
	s_add_u32 s12, s12, 0x40000
	s_addc_u32 s13, s13, 0
	v_mul_f32_e32 v9, v8, v9
	s_waitcnt vmcnt(40)
	v_fmac_f32_e32 v9, v3, v53
	v_mul_f32_e32 v10, v0, v9
	v_cvt_pk_bf16_f32 v10, v10, v10
	global_store_short v21, v10, s[12:13]
	s_add_u32 s12, s12, 0x40000
	s_addc_u32 s13, s13, 0
	v_mul_f32_e32 v9, v8, v9
	s_waitcnt vmcnt(32)
	v_fmac_f32_e32 v9, v3, v54
	v_mul_f32_e32 v11, v0, v9
	v_cvt_pk_bf16_f32 v11, v11, v11
	global_store_short v21, v11, s[12:13]
	s_add_u32 s12, s12, 0x40000
	s_addc_u32 s13, s13, 0
	v_mul_f32_e32 v9, v8, v9
	s_waitcnt vmcnt(32)
	v_fmac_f32_e32 v9, v3, v55
	v_mul_f32_e32 v10, v0, v9
	v_cvt_pk_bf16_f32 v10, v10, v10
	global_store_short v21, v10, s[12:13]
	s_add_u32 s12, s12, 0x40000
	s_addc_u32 s13, s13, 0
	v_mul_f32_e32 v9, v8, v9
	s_waitcnt vmcnt(32)
	v_fmac_f32_e32 v9, v3, v56
	v_mul_f32_e32 v11, v0, v9
	v_cvt_pk_bf16_f32 v11, v11, v11
	global_store_short v21, v11, s[12:13]
	s_add_u32 s12, s12, 0x40000
	s_addc_u32 s13, s13, 0
	v_mul_f32_e32 v9, v8, v9
	s_waitcnt vmcnt(32)
	v_fmac_f32_e32 v9, v3, v57
	v_mul_f32_e32 v10, v0, v9
	v_cvt_pk_bf16_f32 v10, v10, v10
	global_store_short v21, v10, s[12:13]
	s_add_u32 s12, s12, 0x40000
	s_addc_u32 s13, s13, 0
	v_mul_f32_e32 v9, v8, v9
	s_waitcnt vmcnt(32)
	v_fmac_f32_e32 v9, v3, v58
	v_mul_f32_e32 v11, v0, v9
	v_cvt_pk_bf16_f32 v11, v11, v11
	global_store_short v21, v11, s[12:13]
	s_add_u32 s12, s12, 0x40000
	s_addc_u32 s13, s13, 0
	v_mul_f32_e32 v9, v8, v9
	s_waitcnt vmcnt(32)
	v_fmac_f32_e32 v9, v3, v59
	v_mul_f32_e32 v10, v0, v9
	v_cvt_pk_bf16_f32 v10, v10, v10
	global_store_short v21, v10, s[12:13]
	s_add_u32 s12, s12, 0x40000
	s_addc_u32 s13, s13, 0
	v_mul_f32_e32 v9, v8, v9
	s_waitcnt vmcnt(32)
	v_fmac_f32_e32 v9, v3, v60
	v_mul_f32_e32 v11, v0, v9
	v_cvt_pk_bf16_f32 v11, v11, v11
	global_store_short v21, v11, s[12:13]
	s_add_u32 s12, s12, 0x40000
	s_addc_u32 s13, s13, 0
	v_mul_f32_e32 v9, v8, v9
	s_waitcnt vmcnt(32)
	v_fmac_f32_e32 v9, v3, v61
	v_readlane_b32 s6, v254, 59
	s_nop 1
	v_add_u32_e32 v2, s6, v2
	v_readlane_b32 s6, v254, 57
	v_readlane_b32 s7, v254, 58
	s_nop 1
	v_lshl_add_u64 v[4:5], v[4:5], 0, s[6:7]
	v_readlane_b32 s6, v254, 61
	v_readlane_b32 s7, v254, 62
	s_nop 1
	v_lshl_add_u64 v[6:7], v[6:7], 0, s[6:7]
	s_mov_b32 s5, 0x1ffff
	v_cmp_lt_i32_e32 vcc, s5, v2
	s_or_b64 s[2:3], vcc, s[2:3]
	s_andn2_b64 exec, exec, s[2:3]
	s_cbranch_execz .LBB0_1447

; __device__ __forceinline__ unsigned xb_add(unsigned* p, unsigned v) { return __hip_atomic_fetch_add(p, v, __ATOMIC_RELAXED, __HIP_MEMORY_SCOPE_AGENT); }
; __device__ __forceinline__ void xcd_barrier(const XcdBarrier& b) {
;     asm volatile("s_waitcnt vmcnt(0)" ::: "memory");
;     __syncthreads();
;     const unsigned long long bp_ = (unsigned long long)b.bar; unsigned blo_ = __builtin_amdgcn_readfirstlane((unsigned)bp_), bhi_ = __builtin_amdgcn_readfirstlane((unsigned)(bp_ >> 32));
;     asm volatile("" : "+s"(blo_), "+s"(bhi_)); unsigned* bar = (unsigned*)(((unsigned long long)bhi_ << 32) | blo_);
;     if (threadIdx.x == 0) {
;         __builtin_amdgcn_s_waitcnt(0);
;         unsigned nloc = b.st[0], nx = b.st[1];
;         if (nloc == 0u) { xcd_barrier_complete(bar, b.x, nloc, nx); b.st[0] = nloc; b.st[1] = nx; }
;         const unsigned old = xb_add(&bar[XB_XSUB(b.x)], 1u);
;         const unsigned gen = old / nloc;
;         if (old + 1u == (gen + 1u) * nloc) {
.LBB0_2827:
	v_mov_b32_e32 v0, 0x22600
	s_waitcnt lgkmcnt(1)
	ds_read2_b32 v[2:3], v0 offset0:70 offset1:71
	ds_read_b32 v0, v250
	s_waitcnt vmcnt(0)
	s_waitcnt lgkmcnt(0)
	s_barrier
	v_readfirstlane_b32 s0, v2
	v_readfirstlane_b32 s1, v3
	s_add_u32 s34, s0, 0x4000
	s_addc_u32 s35, s1, 0
	v_readfirstlane_b32 s5, v0
	s_mov_b64 s[36:37], exec
	v_readlane_b32 s0, v254, 3
	v_readlane_b32 s1, v254, 4
	s_and_b64 s[0:1], s[36:37], s[0:1]
	s_mov_b64 exec, s[0:1]
	s_cbranch_execz .LBB0_2857
	s_waitcnt vmcnt(0) expcnt(0) lgkmcnt(0)
	buffer_inv sc1
	ds_read_b32 v2, v252
	ds_read_b32 v0, v253
	s_waitcnt lgkmcnt(1)
	v_cmp_ne_u32_e32 vcc, 0, v2
	s_cbranch_vccnz .LBB0_2842
	v_readlane_b32 s0, v254, 0
	v_readlane_b32 s1, v254, 1
	s_load_dwordx2 s[6:7], s[0:1], 0x4
	s_add_u32 s0, s34, 0x1000
	s_addc_u32 s1, s35, 0
	s_add_u32 s2, s34, 0x1100
	s_addc_u32 s3, s35, 0
	s_waitcnt lgkmcnt(0)
	s_mul_i32 s28, s6, s96
	s_add_u32 s6, s34, 0x1200
	s_mul_i32 s28, s28, s7
	s_addc_u32 s7, s35, 0
	s_add_u32 s8, s34, 0x1300
	s_addc_u32 s9, s35, 0
	s_mov_b32 s29, 1
	s_mov_b64 s[10:11], 0
	s_branch .LBB0_2832

; __device__ __forceinline__ unsigned xb_add(unsigned* p, unsigned v) { return __hip_atomic_fetch_add(p, v, __ATOMIC_RELAXED, __HIP_MEMORY_SCOPE_AGENT); }
; __device__ __forceinline__ void xcd_barrier(const XcdBarrier& b) {
;     asm volatile("s_waitcnt vmcnt(0)" ::: "memory");
;     __syncthreads();
;     const unsigned long long bp_ = (unsigned long long)b.bar; unsigned blo_ = __builtin_amdgcn_readfirstlane((unsigned)bp_), bhi_ = __builtin_amdgcn_readfirstlane((unsigned)(bp_ >> 32));
;     asm volatile("" : "+s"(blo_), "+s"(bhi_)); unsigned* bar = (unsigned*)(((unsigned long long)bhi_ << 32) | blo_);
;     if (threadIdx.x == 0) {
;         __builtin_amdgcn_s_waitcnt(0);
;         unsigned nloc = b.st[0], nx = b.st[1];
;         if (nloc == 0u) { xcd_barrier_complete(bar, b.x, nloc, nx); b.st[0] = nloc; b.st[1] = nx; }
;         const unsigned old = xb_add(&bar[XB_XSUB(b.x)], 1u);
;         const unsigned gen = old / nloc;
;         if (old + 1u == (gen + 1u) * nloc) {
.LBB0_3623:
	v_mov_b32_e32 v0, 0x22600
	s_waitcnt vmcnt(11)
	ds_read2_b32 v[2:3], v0 offset0:70 offset1:71
	ds_read_b32 v0, v250
	s_waitcnt vmcnt(0)
	s_waitcnt lgkmcnt(0)
	s_barrier
	v_readfirstlane_b32 s0, v2
	v_readfirstlane_b32 s1, v3
	s_add_u32 s34, s0, 0x4000
	s_addc_u32 s35, s1, 0
	v_readfirstlane_b32 s5, v0
	s_mov_b64 s[36:37], exec
	v_readlane_b32 s0, v254, 3
	v_readlane_b32 s1, v254, 4
	s_and_b64 s[0:1], s[36:37], s[0:1]
	s_mov_b64 exec, s[0:1]
	s_cbranch_execz .LBB0_3653
	s_waitcnt vmcnt(0) expcnt(0) lgkmcnt(0)
	buffer_inv sc1
	ds_read_b32 v2, v252
	ds_read_b32 v0, v253
	s_waitcnt lgkmcnt(1)
	v_cmp_ne_u32_e32 vcc, 0, v2
	s_cbranch_vccnz .LBB0_3638
	v_readlane_b32 s0, v254, 0
	v_readlane_b32 s1, v254, 1
	s_load_dwordx2 s[6:7], s[0:1], 0x4
	s_add_u32 s0, s34, 0x1000
	s_addc_u32 s1, s35, 0
	s_add_u32 s2, s34, 0x1100
	s_addc_u32 s3, s35, 0
	s_waitcnt lgkmcnt(0)
	s_mul_i32 s28, s6, s96
	s_add_u32 s6, s34, 0x1200
	s_mul_i32 s28, s28, s7
	s_addc_u32 s7, s35, 0
	s_add_u32 s8, s34, 0x1300
	s_addc_u32 s9, s35, 0
	s_mov_b32 s29, 1
	s_mov_b64 s[10:11], 0
	s_branch .LBB0_3628

; __device__ __forceinline__ unsigned xb_add(unsigned* p, unsigned v) { return __hip_atomic_fetch_add(p, v, __ATOMIC_RELAXED, __HIP_MEMORY_SCOPE_AGENT); }
; __device__ __forceinline__ void xcd_barrier(const XcdBarrier& b) {
;     ...
;     if (threadIdx.x == 0) {
;         __builtin_amdgcn_s_waitcnt(0);
;         unsigned nloc = b.st[0], nx = b.st[1];
;         if (nloc == 0u) { xcd_barrier_complete(bar, b.x, nloc, nx); b.st[0] = nloc; b.st[1] = nx; }
;         const unsigned old = xb_add(&bar[XB_XSUB(b.x)], 1u);
;         const unsigned gen = old / nloc;
;         if (old + 1u == (gen + 1u) * nloc) {
.LBB0_3705:
	s_waitcnt vmcnt(0) expcnt(0) lgkmcnt(0)
	buffer_inv sc1
	ds_read_b32 v2, v252
	ds_read_b32 v0, v253
	s_waitcnt lgkmcnt(1)
	v_cmp_ne_u32_e32 vcc, 0, v2
	s_cbranch_vccnz .LBB0_3719
	v_readlane_b32 s0, v254, 0
	v_readlane_b32 s1, v254, 1
	s_load_dwordx2 s[6:7], s[0:1], 0x4
	s_add_u32 s0, s34, 0x1000
	s_addc_u32 s1, s35, 0
	s_add_u32 s2, s34, 0x1100
	s_addc_u32 s3, s35, 0
	s_waitcnt lgkmcnt(0)
	s_mul_i32 s28, s6, s96
	s_add_u32 s6, s34, 0x1200
	s_mul_i32 s28, s28, s7
	s_addc_u32 s7, s35, 0
	s_add_u32 s8, s34, 0x1300
	s_addc_u32 s9, s35, 0
	s_mov_b32 s29, 1
	s_mov_b64 s[10:11], 0
	s_branch .LBB0_3709
